# speedup vs baseline: 1.0685x; 1.0175x over previous
; __device__ __forceinline__ float bflo(unsigned u) { return __uint_as_float(u << 16); }
; __device__ __forceinline__ float bfhi(unsigned u) { return __uint_as_float(u & 0xffff0000u); }
; __device__ void phase_peer(const Params& p, int l, float* xout, char* smem) {
;     ...
;     for (int i = 0; i < 4; ++i) {
;       unsigned uu[4] = {xraw[i][0], xraw[i][1], xraw[i][2], xraw[i][3]};
; #pragma unroll
;       for (int j = 0; j < 4; ++j) { xf2[i * 4 + j][0] = bflo(uu[j]); xf2[i * 4 + j][1] = bfhi(uu[j]); }
;     }
;     f32x2 acc2[16];
; #pragma unroll
;     for (int j = 0; j < 16; ++j) acc2[j] = (f32x2){0.f, 0.f};
;     if ((lane & 7) == 0) {
; #pragma unroll
;       for (int k = 0; k < 16; ++k) { sel_e[(lane >> 3) * 16 + k] = ex[k]; sel_g[(lane >> 3) * 16 + k] = gate[k]; }
;     }
;     ...
;     {
;       u32x4 uA[PB], uB[PB]; u32x2 vA[PB][3], vB[PB][3];
;       unsigned char suA[PB], suB[PB], svA[PB], svB[PB];
;       float gA[PB], gB[PB];
;       PEER_LOAD(uA, vA, suA, svA, gA, 0);
.LBB0_1260:
	s_or_b64 exec, exec, s[40:41]
	s_waitcnt lgkmcnt(0)
	v_mbcnt_lo_u32_b32 v16, -1, 0
	v_mbcnt_hi_u32_b32 v16, -1, v16
	v_lshl_add_u32 v17, v16, 2, v79
	ds_read2st64_b32 v[18:19], v17 offset1:1
	ds_read2st64_b32 v[20:21], v17 offset0:2 offset1:3
	s_waitcnt lgkmcnt(0)
	v_lshl_add_u32 v22, v18, 7, v16
	v_lshl_add_u32 v23, v19, 7, v16
	v_add_u32_e32 v23, 64, v23
	v_mov_b32_e32 v24, 0
	v_mov_b32_e32 v25, 0
	s_mov_b32 s28, 0
.Lmy_sort:
	v_readlane_b32 s66, v22, s28
	v_readlane_b32 s67, v23, s28
	s_add_i32 s28, s28, 1
	s_nop 1
	v_cmp_lt_u32_e64 s[4:5], s66, v22
	v_cmp_lt_u32_e64 s[40:41], s66, v23
	v_cmp_lt_u32_e64 s[68:69], s67, v22
	v_cmp_lt_u32_e64 s[72:73], s67, v23
	v_addc_co_u32_e64 v24, s[98:99], 0, v24, s[4:5]
	v_addc_co_u32_e64 v25, s[98:99], 0, v25, s[40:41]
	v_addc_co_u32_e64 v24, s[98:99], 0, v24, s[68:69]
	v_addc_co_u32_e64 v25, s[98:99], 0, v25, s[72:73]
	s_cmp_lt_u32 s28, 64
	s_cbranch_scc1 .Lmy_sort
	v_lshl_add_u32 v24, v24, 2, v79
	v_lshl_add_u32 v25, v25, 2, v79
	ds_write_b32 v24, v18
	ds_write_b32 v24, v20 offset:512
	ds_write_b32 v25, v19
	ds_write_b32 v25, v21 offset:512
	s_waitcnt lgkmcnt(0)
	s_waitcnt vmcnt(0)
	v_lshlrev_b32_e32 v93, 16, v13
	v_lshlrev_b32_e32 v92, 16, v12
	v_and_b32_e32 v95, 0xffff0000, v13
	v_and_b32_e32 v94, 0xffff0000, v12
	v_lshlrev_b32_e32 v97, 16, v15
	v_lshlrev_b32_e32 v96, 16, v14
	v_and_b32_e32 v99, 0xffff0000, v15
	v_and_b32_e32 v98, 0xffff0000, v14
	ds_read2st64_b64 v[12:15], v79 offset1:1
	v_lshlrev_b64 v[90:91], 11, v[72:73]
	v_lshlrev_b32_e32 v101, 16, v9
	v_lshlrev_b32_e32 v100, 16, v8
	v_and_b32_e32 v109, 0xffff0000, v9
	s_waitcnt lgkmcnt(0)
	v_readfirstlane_b32 s4, v12
	s_mul_i32 s11, s4, 0xa80
	s_mul_hi_i32 s5, s4, 0xa80
	s_add_u32 s40, s42, s11
	s_addc_u32 s41, s43, s5
	s_mul_hi_i32 s5, s4, 0xa80
	s_mulk_i32 s4, 0xa80
	s_add_u32 s66, s90, s4
	v_readfirstlane_b32 s4, v13
	v_and_b32_e32 v108, 0xffff0000, v8
	s_addc_u32 s67, s91, s5
	v_lshlrev_b32_e32 v73, 4, v74
	v_lshl_add_u64 v[8:9], s[40:41], 0, v[74:75]
	s_mul_i32 s11, s4, 0xa80
	global_load_dwordx4 v[56:59], v73, s[40:41]
	global_load_ubyte v205, v[8:9], off offset:1024
	s_mul_hi_i32 s5, s4, 0xa80
	s_add_u32 s40, s42, s11
	v_lshlrev_b32_e32 v176, 3, v74
	v_lshl_add_u64 v[8:9], s[66:67], 0, v[74:75]
	s_addc_u32 s41, s43, s5
	s_mul_hi_i32 s5, s4, 0xa80
	s_mulk_i32 s4, 0xa80
	global_load_dwordx2 v[32:33], v176, s[66:67]
	global_load_dwordx2 v[34:35], v176, s[66:67] offset:512
	global_load_dwordx2 v[36:37], v176, s[66:67] offset:1024
	global_load_ubyte v203, v[8:9], off offset:1536
	s_add_u32 s66, s90, s4
	v_lshl_add_u64 v[8:9], s[40:41], 0, v[74:75]
	s_addc_u32 s67, s91, s5
	global_load_dwordx4 v[60:63], v73, s[40:41]
	global_load_ubyte v206, v[8:9], off offset:1024
	global_load_dwordx2 v[38:39], v176, s[66:67]
	global_load_dwordx2 v[40:41], v176, s[66:67] offset:512
	global_load_dwordx2 v[42:43], v176, s[66:67] offset:1024
	v_lshl_add_u64 v[8:9], s[66:67], 0, v[74:75]
	global_load_ubyte v204, v[8:9], off offset:1536
	v_lshlrev_b32_e32 v113, 16, v11
	v_lshlrev_b32_e32 v112, 16, v10
	v_and_b32_e32 v115, 0xffff0000, v11
	v_and_b32_e32 v114, 0xffff0000, v10
	v_lshlrev_b32_e32 v117, 16, v5
	v_lshlrev_b32_e32 v116, 16, v4
	v_and_b32_e32 v119, 0xffff0000, v5
	v_and_b32_e32 v118, 0xffff0000, v4
	v_lshlrev_b32_e32 v121, 16, v7
	v_lshlrev_b32_e32 v120, 16, v6
	v_and_b32_e32 v123, 0xffff0000, v7
	v_and_b32_e32 v122, 0xffff0000, v6
	v_lshlrev_b32_e32 v125, 16, v1
	v_lshlrev_b32_e32 v124, 16, v0
	v_and_b32_e32 v127, 0xffff0000, v1
	v_and_b32_e32 v126, 0xffff0000, v0
	v_lshlrev_b32_e32 v131, 16, v3
	v_lshlrev_b32_e32 v130, 16, v2
	v_and_b32_e32 v133, 0xffff0000, v3
	v_and_b32_e32 v132, 0xffff0000, v2
	v_mov_b32_e32 v156, 0
	v_mov_b32_e32 v102, v92
	v_mov_b32_e32 v103, v94
	v_mov_b32_e32 v104, v93
	v_mov_b32_e32 v105, v95
	v_mov_b32_e32 v106, v96
	v_mov_b32_e32 v107, v98
	v_mov_b32_e32 v110, v97
	v_mov_b32_e32 v111, v99
	v_mov_b32_e32 v128, v100
	v_mov_b32_e32 v129, v108
	v_mov_b32_e32 v134, v101
	v_mov_b32_e32 v135, v109
	v_mov_b32_e32 v136, v112
	v_mov_b32_e32 v137, v114
	v_mov_b32_e32 v138, v113
	v_mov_b32_e32 v139, v115
	v_mov_b32_e32 v140, v116
	v_mov_b32_e32 v141, v118
	v_mov_b32_e32 v142, v117
	v_mov_b32_e32 v143, v119
	v_mov_b32_e32 v144, v120
	v_mov_b32_e32 v145, v122
	v_mov_b32_e32 v146, v121
	v_mov_b32_e32 v147, v123
	v_mov_b32_e32 v148, v124
	v_mov_b32_e32 v149, v126
	v_mov_b32_e32 v150, v125
	v_mov_b32_e32 v151, v127
	v_mov_b32_e32 v152, v130
	v_mov_b32_e32 v153, v132
	v_mov_b32_e32 v154, v131
	v_mov_b32_e32 v155, v133
	v_readfirstlane_b32 s40, v14
	v_readfirstlane_b32 s11, v15
	s_mov_b32 s66, -4
	v_mov_b32_e32 v202, v201
	v_mov_b32_e32 v157, v156
	v_mov_b32_e32 v174, v156
	v_mov_b32_e32 v175, v156
	v_mov_b32_e32 v160, v156
	v_mov_b32_e32 v161, v156
	v_mov_b32_e32 v188, v156
	v_mov_b32_e32 v189, v156
	v_mov_b32_e32 v158, v156
	v_mov_b32_e32 v159, v156
	v_mov_b32_e32 v172, v156
	v_mov_b32_e32 v173, v156
	v_mov_b32_e32 v164, v156
	v_mov_b32_e32 v165, v156
	v_mov_b32_e32 v192, v156
	v_mov_b32_e32 v193, v156
	v_mov_b32_e32 v162, v156
	v_mov_b32_e32 v163, v156
	v_mov_b32_e32 v190, v156
	v_mov_b32_e32 v191, v156
	v_mov_b32_e32 v168, v156
	v_mov_b32_e32 v169, v156
	v_mov_b32_e32 v194, v156
	v_mov_b32_e32 v195, v156
	v_mov_b32_e32 v166, v156
	v_mov_b32_e32 v167, v156
	v_mov_b32_e32 v186, v156
	v_mov_b32_e32 v187, v156
	v_mov_b32_e32 v170, v156
	v_mov_b32_e32 v171, v156
	v_mov_b32_e32 v196, v156
	v_mov_b32_e32 v197, v156
; __device__ void phase_peer(const Params& p, int l, float* xout, char* smem) {
;     ...
;       for (int e0 = 0; e0 < 128; e0 += 2 * PB) {
;         __builtin_amdgcn_s_setprio(3); PEER_LOAD(uB, vB, suB, svB, gB, e0 + PB); __builtin_amdgcn_s_setprio(2);
;         PEER_COMPUTE(uA, vA, suA, svA, gA);
.LBB0_1261:
	s_add_i32 s28, s66, 4
	s_setprio 3
	ds_read2st64_b64 v[0:3], v202 offset1:1
	s_waitcnt lgkmcnt(0)
	v_readfirstlane_b32 s4, v0
	s_mul_i32 s41, s4, 0xa80
	s_mul_hi_i32 s5, s4, 0xa80
	s_add_u32 s68, s42, s41
	s_mul_hi_i32 s67, s4, 0xa80
	s_mulk_i32 s4, 0xa80
	s_addc_u32 s69, s43, s5
	s_add_u32 s72, s90, s4
	v_readfirstlane_b32 s4, v1
	s_addc_u32 s73, s91, s67
	s_mul_i32 s41, s4, 0xa80
	global_load_dwordx4 v[64:67], v73, s[68:69]
	v_lshl_add_u64 v[4:5], s[68:69], 0, v[74:75]
	s_mul_hi_i32 s5, s4, 0xa80
	s_add_u32 s68, s42, s41
	s_addc_u32 s69, s43, s5
	s_mul_hi_i32 s5, s4, 0xa80
	s_mulk_i32 s4, 0xa80
	global_load_ubyte v231, v[4:5], off offset:1024
	global_load_dwordx2 v[50:51], v176, s[72:73]
	global_load_dwordx2 v[52:53], v176, s[72:73] offset:512
	global_load_dwordx2 v[54:55], v176, s[72:73] offset:1024
	v_lshl_add_u64 v[4:5], s[72:73], 0, v[74:75]
	s_add_u32 s72, s90, s4
	v_lshl_add_u64 v[0:1], s[68:69], 0, v[74:75]
	global_load_ubyte v238, v[4:5], off offset:1536
	s_addc_u32 s73, s91, s5
	global_load_dwordx4 v[68:71], v73, s[68:69]
	global_load_ubyte v239, v[0:1], off offset:1024
	global_load_dwordx2 v[44:45], v176, s[72:73]
	global_load_dwordx2 v[46:47], v176, s[72:73] offset:512
	global_load_dwordx2 v[48:49], v176, s[72:73] offset:1024
	v_lshl_add_u64 v[0:1], s[72:73], 0, v[74:75]
	global_load_ubyte v208, v[0:1], off offset:1536
	v_readfirstlane_b32 s67, v2
	v_readfirstlane_b32 s41, v3
	s_setprio 2
	s_waitcnt vmcnt(22)
	v_lshlrev_b32_sdwa v6, v230, v205 dst_sel:DWORD dst_unused:UNUSED_PAD src0_sel:DWORD src1_sel:BYTE_0
	v_cvt_scalef32_pk_f32_fp4 v[0:1], v56, v6
	v_pk_fma_f32 v[0:1], v[0:1], v[102:103], 0 op_sel_hi:[1,1,0]
	v_cvt_scalef32_pk_f32_fp4 v[2:3], v56, v6 op_sel:[1,0,0]
	v_cvt_scalef32_pk_f32_fp4 v[4:5], v56, v6 op_sel:[0,1,0]
	v_pk_fma_f32 v[2:3], v[2:3], v[104:105], 0 op_sel_hi:[1,1,0]
	v_pk_fma_f32 v[0:1], v[4:5], v[106:107], v[0:1]
	v_cvt_scalef32_pk_f32_fp4 v[4:5], v56, v6 op_sel:[1,1,0]
	v_pk_fma_f32 v[2:3], v[4:5], v[110:111], v[2:3]
	v_cvt_scalef32_pk_f32_fp4 v[4:5], v57, v6
	v_pk_fma_f32 v[0:1], v[4:5], v[128:129], v[0:1]
	v_cvt_scalef32_pk_f32_fp4 v[4:5], v57, v6 op_sel:[1,0,0]
	v_pk_fma_f32 v[2:3], v[4:5], v[134:135], v[2:3]
	v_cvt_scalef32_pk_f32_fp4 v[4:5], v57, v6 op_sel:[0,1,0]
	v_pk_fma_f32 v[0:1], v[4:5], v[136:137], v[0:1]
	v_cvt_scalef32_pk_f32_fp4 v[4:5], v57, v6 op_sel:[1,1,0]
	v_pk_fma_f32 v[2:3], v[4:5], v[138:139], v[2:3]
	v_cvt_scalef32_pk_f32_fp4 v[4:5], v58, v6
	v_pk_fma_f32 v[0:1], v[4:5], v[140:141], v[0:1]
	v_cvt_scalef32_pk_f32_fp4 v[4:5], v58, v6 op_sel:[1,0,0]
	v_pk_fma_f32 v[2:3], v[4:5], v[142:143], v[2:3]
	v_cvt_scalef32_pk_f32_fp4 v[4:5], v58, v6 op_sel:[0,1,0]
	v_pk_fma_f32 v[0:1], v[4:5], v[144:145], v[0:1]
	v_cvt_scalef32_pk_f32_fp4 v[4:5], v58, v6 op_sel:[1,1,0]
	v_pk_fma_f32 v[2:3], v[4:5], v[146:147], v[2:3]
	v_cvt_scalef32_pk_f32_fp4 v[4:5], v59, v6
	v_pk_fma_f32 v[0:1], v[4:5], v[148:149], v[0:1]
	v_cvt_scalef32_pk_f32_fp4 v[4:5], v59, v6 op_sel:[1,0,0]
	v_pk_fma_f32 v[2:3], v[4:5], v[150:151], v[2:3]
	v_cvt_scalef32_pk_f32_fp4 v[4:5], v59, v6 op_sel:[0,1,0]
	v_pk_fma_f32 v[0:1], v[4:5], v[152:153], v[0:1]
	v_cvt_scalef32_pk_f32_fp4 v[4:5], v59, v6 op_sel:[1,1,0]
	v_pk_fma_f32 v[2:3], v[4:5], v[154:155], v[2:3]
	s_waitcnt vmcnt(16)
	v_lshlrev_b32_sdwa v7, v230, v206 dst_sel:DWORD dst_unused:UNUSED_PAD src0_sel:DWORD src1_sel:BYTE_0
	v_pk_add_f32 v[0:1], v[0:1], v[2:3]
	v_cvt_scalef32_pk_f32_fp4 v[2:3], v60, v7 op_sel:[1,0,0]
	v_add_f32_e32 v6, v0, v1
	v_cvt_scalef32_pk_f32_fp4 v[0:1], v60, v7
	v_pk_fma_f32 v[0:1], v[0:1], v[102:103], 0 op_sel_hi:[1,1,0]
	v_cvt_scalef32_pk_f32_fp4 v[4:5], v60, v7 op_sel:[0,1,0]
	v_pk_fma_f32 v[2:3], v[2:3], v[104:105], 0 op_sel_hi:[1,1,0]
	v_pk_fma_f32 v[0:1], v[4:5], v[106:107], v[0:1]
	v_cvt_scalef32_pk_f32_fp4 v[4:5], v60, v7 op_sel:[1,1,0]
	v_pk_fma_f32 v[2:3], v[4:5], v[110:111], v[2:3]
	v_cvt_scalef32_pk_f32_fp4 v[4:5], v61, v7
	v_pk_fma_f32 v[0:1], v[4:5], v[128:129], v[0:1]
	v_cvt_scalef32_pk_f32_fp4 v[4:5], v61, v7 op_sel:[1,0,0]
	v_pk_fma_f32 v[2:3], v[4:5], v[134:135], v[2:3]
	v_cvt_scalef32_pk_f32_fp4 v[4:5], v61, v7 op_sel:[0,1,0]
	v_pk_fma_f32 v[0:1], v[4:5], v[136:137], v[0:1]
	v_cvt_scalef32_pk_f32_fp4 v[4:5], v61, v7 op_sel:[1,1,0]
	v_pk_fma_f32 v[2:3], v[4:5], v[138:139], v[2:3]
	v_cvt_scalef32_pk_f32_fp4 v[4:5], v62, v7
	v_pk_fma_f32 v[0:1], v[4:5], v[140:141], v[0:1]
	v_cvt_scalef32_pk_f32_fp4 v[4:5], v62, v7 op_sel:[1,0,0]
	v_pk_fma_f32 v[2:3], v[4:5], v[142:143], v[2:3]
	v_cvt_scalef32_pk_f32_fp4 v[4:5], v62, v7 op_sel:[0,1,0]
	v_pk_fma_f32 v[0:1], v[4:5], v[144:145], v[0:1]
	v_cvt_scalef32_pk_f32_fp4 v[4:5], v62, v7 op_sel:[1,1,0]
	v_pk_fma_f32 v[2:3], v[4:5], v[146:147], v[2:3]
	v_cvt_scalef32_pk_f32_fp4 v[4:5], v63, v7
	v_pk_fma_f32 v[0:1], v[4:5], v[148:149], v[0:1]
	v_cvt_scalef32_pk_f32_fp4 v[4:5], v63, v7 op_sel:[1,0,0]
	v_pk_fma_f32 v[2:3], v[4:5], v[150:151], v[2:3]
	v_cvt_scalef32_pk_f32_fp4 v[4:5], v63, v7 op_sel:[0,1,0]
	v_pk_fma_f32 v[0:1], v[4:5], v[152:153], v[0:1]
	v_cvt_scalef32_pk_f32_fp4 v[4:5], v63, v7 op_sel:[1,1,0]
	v_pk_fma_f32 v[2:3], v[4:5], v[154:155], v[2:3]
	v_lshlrev_b32_sdwa v57, v230, v203 dst_sel:DWORD dst_unused:UNUSED_PAD src0_sel:DWORD src1_sel:BYTE_0
	v_pk_add_f32 v[0:1], v[0:1], v[2:3]
	s_nop 0
	v_add_f32_e32 v0, v0, v1
	v_add_f32_dpp v1, v6, v6 quad_perm:[1,0,3,2] row_mask:0xf bank_mask:0xf bound_ctrl:1
	s_nop 0
	v_add_f32_dpp v0, v0, v0 quad_perm:[1,0,3,2] row_mask:0xf bank_mask:0xf bound_ctrl:1
	v_add_f32_dpp v1, v1, v1 quad_perm:[2,3,0,1] row_mask:0xf bank_mask:0xf bound_ctrl:1
	s_nop 0
	v_add_f32_dpp v0, v0, v0 quad_perm:[2,3,0,1] row_mask:0xf bank_mask:0xf bound_ctrl:1
; __device__ void phase_peer(const Params& p, int l, float* xout, char* smem) {
;     ...
;         __builtin_amdgcn_s_setprio(3); PEER_LOAD(uA, vA, suA, svA, gA, e0 + 2 * PB); __builtin_amdgcn_s_setprio(2);
	v_add_f32_dpp v1, v1, v1 row_half_mirror row_mask:0xf bank_mask:0xf bound_ctrl:1
	s_nop 0
	v_add_f32_dpp v0, v0, v0 row_half_mirror row_mask:0xf bank_mask:0xf bound_ctrl:1
	v_add_f32_dpp v1, v1, v1 row_mirror row_mask:0xf bank_mask:0xf bound_ctrl:1
	s_nop 0
	v_add_f32_dpp v0, v0, v0 row_mirror row_mask:0xf bank_mask:0xf bound_ctrl:1
	v_add_f32_dpp v1, v1, v1 row_bcast:15 row_mask:0xf bank_mask:0xf bound_ctrl:1
	s_nop 0
	v_add_f32_dpp v0, v0, v0 row_bcast:15 row_mask:0xf bank_mask:0xf bound_ctrl:1
	v_add_f32_dpp v1, v1, v1 row_bcast:31 row_mask:0xf bank_mask:0xf bound_ctrl:1
	s_nop 0
	v_readlane_b32 s4, v1, 63
	v_add_f32_dpp v0, v0, v0 row_bcast:31 row_mask:0xf bank_mask:0xf bound_ctrl:1
	s_nop 0
	v_mul_f32_e64 v1, s4, s4
	v_fmamk_f32 v1, v1, 0x3dd2d3e7, v213
	v_mul_f32_e32 v1, s4, v1
	v_exp_f32_e32 v1, v1
	v_readlane_b32 s5, v0, 63
	v_add_f32_e32 v1, 1.0, v1
	v_rcp_f32_e32 v1, v1
	s_nop 0
	v_fma_f32 v0, -s4, v1, s4
	v_mul_f32_e32 v56, s40, v0
	v_cvt_scalef32_pk32_f32_fp6 v[0:31], v[32:37], v57
	v_pk_fma_f32 v[32:33], v[56:57], v[0:1], v[196:197] op_sel_hi:[0,1,1]
	v_mul_f32_e64 v0, s5, s5
	v_fmamk_f32 v0, v0, 0x3dd2d3e7, v213
	v_mul_f32_e32 v0, s5, v0
	v_exp_f32_e32 v0, v0
	v_pk_fma_f32 v[34:35], v[56:57], v[2:3], v[170:171] op_sel_hi:[0,1,1]
	v_pk_fma_f32 v[36:37], v[56:57], v[4:5], v[186:187] op_sel_hi:[0,1,1]
	v_pk_fma_f32 v[58:59], v[56:57], v[6:7], v[166:167] op_sel_hi:[0,1,1]
	v_add_f32_e32 v0, 1.0, v0
	v_rcp_f32_e32 v0, v0
	v_pk_fma_f32 v[60:61], v[56:57], v[8:9], v[194:195] op_sel_hi:[0,1,1]
	v_pk_fma_f32 v[62:63], v[56:57], v[10:11], v[168:169] op_sel_hi:[0,1,1]
	v_pk_fma_f32 v[166:167], v[56:57], v[12:13], v[190:191] op_sel_hi:[0,1,1]
	v_pk_fma_f32 v[162:163], v[56:57], v[14:15], v[162:163] op_sel_hi:[0,1,1]
	v_pk_fma_f32 v[194:195], v[56:57], v[16:17], v[192:193] op_sel_hi:[0,1,1]
	v_pk_fma_f32 v[164:165], v[56:57], v[18:19], v[164:165] op_sel_hi:[0,1,1]
	v_pk_fma_f32 v[210:211], v[56:57], v[20:21], v[172:173] op_sel_hi:[0,1,1]
	v_pk_fma_f32 v[158:159], v[56:57], v[22:23], v[158:159] op_sel_hi:[0,1,1]
	v_pk_fma_f32 v[232:233], v[56:57], v[24:25], v[188:189] op_sel_hi:[0,1,1]
	v_pk_fma_f32 v[234:235], v[56:57], v[26:27], v[160:161] op_sel_hi:[0,1,1]
	v_pk_fma_f32 v[236:237], v[56:57], v[28:29], v[174:175] op_sel_hi:[0,1,1]
	v_pk_fma_f32 v[56:57], v[56:57], v[30:31], v[156:157] op_sel_hi:[0,1,1]
	v_fma_f32 v0, -s5, v0, s5
	s_waitcnt vmcnt(12)
	v_lshlrev_b32_sdwa v156, v230, v204 dst_sel:DWORD dst_unused:UNUSED_PAD src0_sel:DWORD src1_sel:BYTE_0
	v_mul_f32_e32 v206, s11, v0
	v_cvt_scalef32_pk32_f32_fp6 v[0:31], v[38:43], v156
	v_pk_fma_f32 v[168:169], v[206:207], v[0:1], v[32:33] op_sel_hi:[0,1,1]
	v_pk_fma_f32 v[170:171], v[206:207], v[2:3], v[34:35] op_sel_hi:[0,1,1]
	v_pk_fma_f32 v[172:173], v[206:207], v[4:5], v[36:37] op_sel_hi:[0,1,1]
	v_pk_fma_f32 v[174:175], v[206:207], v[6:7], v[58:59] op_sel_hi:[0,1,1]
	v_pk_fma_f32 v[186:187], v[206:207], v[8:9], v[60:61] op_sel_hi:[0,1,1]
	v_pk_fma_f32 v[188:189], v[206:207], v[10:11], v[62:63] op_sel_hi:[0,1,1]
	v_pk_fma_f32 v[190:191], v[206:207], v[12:13], v[166:167] op_sel_hi:[0,1,1]
	v_pk_fma_f32 v[192:193], v[206:207], v[14:15], v[162:163] op_sel_hi:[0,1,1]
	v_pk_fma_f32 v[194:195], v[206:207], v[16:17], v[194:195] op_sel_hi:[0,1,1]
	v_pk_fma_f32 v[196:197], v[206:207], v[18:19], v[164:165] op_sel_hi:[0,1,1]
	v_pk_fma_f32 v[156:157], v[206:207], v[20:21], v[210:211] op_sel_hi:[0,1,1]
	v_pk_fma_f32 v[158:159], v[206:207], v[22:23], v[158:159] op_sel_hi:[0,1,1]
	v_pk_fma_f32 v[160:161], v[206:207], v[24:25], v[232:233] op_sel_hi:[0,1,1]
	v_pk_fma_f32 v[162:163], v[206:207], v[26:27], v[234:235] op_sel_hi:[0,1,1]
	v_pk_fma_f32 v[164:165], v[206:207], v[28:29], v[236:237] op_sel_hi:[0,1,1]
	v_pk_fma_f32 v[166:167], v[206:207], v[30:31], v[56:57] op_sel_hi:[0,1,1]
	s_setprio 3
	s_add_i32 s4, s66, 8
	s_min_u32 s4, s4, 0x7f
	v_lshl_add_u32 v0, s4, 2, v79
	ds_read2st64_b32 v[0:1], v0 offset1:2
	s_waitcnt lgkmcnt(0)
	v_readfirstlane_b32 s4, v0
	s_mul_i32 s11, s4, 0xa80
	s_mul_hi_i32 s5, s4, 0xa80
	s_add_u32 s68, s42, s11
	s_mul_hi_i32 s40, s4, 0xa80
	s_mulk_i32 s4, 0xa80
	s_addc_u32 s69, s43, s5
	s_add_u32 s72, s90, s4
	s_addc_u32 s73, s91, s40
	s_min_u32 s4, s28, 0x7a
	v_lshl_add_u64 v[2:3], s[68:69], 0, v[74:75]
	v_lshl_add_u32 v0, s4, 2, v79
	global_load_dwordx4 v[56:59], v73, s[68:69]
	global_load_ubyte v205, v[2:3], off offset:1024
	global_load_dwordx2 v[32:33], v176, s[72:73]
	ds_read2_b32 v[2:3], v0 offset0:5 offset1:133
	v_lshl_add_u64 v[4:5], s[72:73], 0, v[74:75]
	global_load_dwordx2 v[34:35], v176, s[72:73] offset:512
	global_load_dwordx2 v[36:37], v176, s[72:73] offset:1024
	global_load_ubyte v203, v[4:5], off offset:1536
	v_readfirstlane_b32 s40, v1
	s_waitcnt lgkmcnt(0)
	v_readfirstlane_b32 s4, v2
	s_mul_i32 s11, s4, 0xa80
	s_mul_hi_i32 s5, s4, 0xa80
	s_add_u32 s68, s42, s11
	s_addc_u32 s69, s43, s5
	s_mul_hi_i32 s5, s4, 0xa80
	s_mulk_i32 s4, 0xa80
	s_add_u32 s72, s90, s4
	v_lshl_add_u64 v[4:5], s[68:69], 0, v[74:75]
	s_addc_u32 s73, s91, s5
	global_load_dwordx4 v[60:63], v73, s[68:69]
	global_load_ubyte v206, v[4:5], off offset:1024
	global_load_dwordx2 v[38:39], v176, s[72:73]
	global_load_dwordx2 v[40:41], v176, s[72:73] offset:512
	global_load_dwordx2 v[42:43], v176, s[72:73] offset:1024
	v_lshl_add_u64 v[4:5], s[72:73], 0, v[74:75]
	global_load_ubyte v204, v[4:5], off offset:1536
	v_readfirstlane_b32 s11, v3
	s_setprio 2
	s_waitcnt vmcnt(22)
; __device__ void phase_peer(const Params& p, int l, float* xout, char* smem) {
;     ...
;         PEER_COMPUTE(uB, vB, suB, svB, gB);
	v_lshlrev_b32_e32 v6, 23, v231
	v_cvt_scalef32_pk_f32_fp4 v[0:1], v64, v6
	v_pk_fma_f32 v[0:1], v[0:1], v[102:103], 0 op_sel_hi:[1,1,0]
	v_cvt_scalef32_pk_f32_fp4 v[2:3], v64, v6 op_sel:[1,0,0]
	v_cvt_scalef32_pk_f32_fp4 v[4:5], v64, v6 op_sel:[0,1,0]
	v_pk_fma_f32 v[2:3], v[2:3], v[104:105], 0 op_sel_hi:[1,1,0]
	v_pk_fma_f32 v[0:1], v[4:5], v[106:107], v[0:1]
	v_cvt_scalef32_pk_f32_fp4 v[4:5], v64, v6 op_sel:[1,1,0]
	v_pk_fma_f32 v[2:3], v[4:5], v[110:111], v[2:3]
	v_cvt_scalef32_pk_f32_fp4 v[4:5], v65, v6
	v_pk_fma_f32 v[0:1], v[4:5], v[128:129], v[0:1]
	v_cvt_scalef32_pk_f32_fp4 v[4:5], v65, v6 op_sel:[1,0,0]
	v_pk_fma_f32 v[2:3], v[4:5], v[134:135], v[2:3]
	v_cvt_scalef32_pk_f32_fp4 v[4:5], v65, v6 op_sel:[0,1,0]
	v_pk_fma_f32 v[0:1], v[4:5], v[136:137], v[0:1]
	v_cvt_scalef32_pk_f32_fp4 v[4:5], v65, v6 op_sel:[1,1,0]
	v_pk_fma_f32 v[2:3], v[4:5], v[138:139], v[2:3]
	v_cvt_scalef32_pk_f32_fp4 v[4:5], v66, v6
	v_pk_fma_f32 v[0:1], v[4:5], v[140:141], v[0:1]
	v_cvt_scalef32_pk_f32_fp4 v[4:5], v66, v6 op_sel:[1,0,0]
	v_pk_fma_f32 v[2:3], v[4:5], v[142:143], v[2:3]
	v_cvt_scalef32_pk_f32_fp4 v[4:5], v66, v6 op_sel:[0,1,0]
	v_pk_fma_f32 v[0:1], v[4:5], v[144:145], v[0:1]
	v_cvt_scalef32_pk_f32_fp4 v[4:5], v66, v6 op_sel:[1,1,0]
	v_pk_fma_f32 v[2:3], v[4:5], v[146:147], v[2:3]
	v_cvt_scalef32_pk_f32_fp4 v[4:5], v67, v6
	v_pk_fma_f32 v[0:1], v[4:5], v[148:149], v[0:1]
	v_cvt_scalef32_pk_f32_fp4 v[4:5], v67, v6 op_sel:[1,0,0]
	v_pk_fma_f32 v[2:3], v[4:5], v[150:151], v[2:3]
	v_cvt_scalef32_pk_f32_fp4 v[4:5], v67, v6 op_sel:[0,1,0]
	v_pk_fma_f32 v[0:1], v[4:5], v[152:153], v[0:1]
	v_cvt_scalef32_pk_f32_fp4 v[4:5], v67, v6 op_sel:[1,1,0]
	v_pk_fma_f32 v[2:3], v[4:5], v[154:155], v[2:3]
	s_waitcnt vmcnt(16)
	v_lshlrev_b32_e32 v7, 23, v239
	v_pk_add_f32 v[0:1], v[0:1], v[2:3]
	v_cvt_scalef32_pk_f32_fp4 v[2:3], v68, v7 op_sel:[1,0,0]
	v_add_f32_e32 v6, v0, v1
	v_cvt_scalef32_pk_f32_fp4 v[0:1], v68, v7
	v_pk_fma_f32 v[0:1], v[0:1], v[102:103], 0 op_sel_hi:[1,1,0]
	v_cvt_scalef32_pk_f32_fp4 v[4:5], v68, v7 op_sel:[0,1,0]
	v_pk_fma_f32 v[2:3], v[2:3], v[104:105], 0 op_sel_hi:[1,1,0]
	v_pk_fma_f32 v[0:1], v[4:5], v[106:107], v[0:1]
	v_cvt_scalef32_pk_f32_fp4 v[4:5], v68, v7 op_sel:[1,1,0]
	v_pk_fma_f32 v[2:3], v[4:5], v[110:111], v[2:3]
	v_cvt_scalef32_pk_f32_fp4 v[4:5], v69, v7
	v_pk_fma_f32 v[0:1], v[4:5], v[128:129], v[0:1]
	v_cvt_scalef32_pk_f32_fp4 v[4:5], v69, v7 op_sel:[1,0,0]
	v_pk_fma_f32 v[2:3], v[4:5], v[134:135], v[2:3]
	v_cvt_scalef32_pk_f32_fp4 v[4:5], v69, v7 op_sel:[0,1,0]
	v_pk_fma_f32 v[0:1], v[4:5], v[136:137], v[0:1]
	v_cvt_scalef32_pk_f32_fp4 v[4:5], v69, v7 op_sel:[1,1,0]
	v_pk_fma_f32 v[2:3], v[4:5], v[138:139], v[2:3]
	v_cvt_scalef32_pk_f32_fp4 v[4:5], v70, v7
	v_pk_fma_f32 v[0:1], v[4:5], v[140:141], v[0:1]
	v_cvt_scalef32_pk_f32_fp4 v[4:5], v70, v7 op_sel:[1,0,0]
	v_pk_fma_f32 v[2:3], v[4:5], v[142:143], v[2:3]
	v_cvt_scalef32_pk_f32_fp4 v[4:5], v70, v7 op_sel:[0,1,0]
	v_pk_fma_f32 v[0:1], v[4:5], v[144:145], v[0:1]
	v_cvt_scalef32_pk_f32_fp4 v[4:5], v70, v7 op_sel:[1,1,0]
	v_pk_fma_f32 v[2:3], v[4:5], v[146:147], v[2:3]
	v_cvt_scalef32_pk_f32_fp4 v[4:5], v71, v7
	v_pk_fma_f32 v[0:1], v[4:5], v[148:149], v[0:1]
	v_cvt_scalef32_pk_f32_fp4 v[4:5], v71, v7 op_sel:[1,0,0]
	v_pk_fma_f32 v[2:3], v[4:5], v[150:151], v[2:3]
	v_cvt_scalef32_pk_f32_fp4 v[4:5], v71, v7 op_sel:[0,1,0]
	v_pk_fma_f32 v[0:1], v[4:5], v[152:153], v[0:1]
	v_cvt_scalef32_pk_f32_fp4 v[4:5], v71, v7 op_sel:[1,1,0]
	v_pk_fma_f32 v[2:3], v[4:5], v[154:155], v[2:3]
	v_lshlrev_b32_e32 v65, 23, v238
	v_pk_add_f32 v[0:1], v[0:1], v[2:3]
	v_add_u32_e32 v202, 16, v202
	v_add_f32_e32 v0, v0, v1
	v_add_f32_dpp v1, v6, v6 quad_perm:[1,0,3,2] row_mask:0xf bank_mask:0xf bound_ctrl:1
	s_cmpk_gt_u32 s28, 0x7b
	v_add_f32_dpp v0, v0, v0 quad_perm:[1,0,3,2] row_mask:0xf bank_mask:0xf bound_ctrl:1
	v_add_f32_dpp v1, v1, v1 quad_perm:[2,3,0,1] row_mask:0xf bank_mask:0xf bound_ctrl:1
	s_mov_b32 s66, s28
	v_add_f32_dpp v0, v0, v0 quad_perm:[2,3,0,1] row_mask:0xf bank_mask:0xf bound_ctrl:1
	v_add_f32_dpp v1, v1, v1 row_half_mirror row_mask:0xf bank_mask:0xf bound_ctrl:1
	s_nop 0
	v_add_f32_dpp v0, v0, v0 row_half_mirror row_mask:0xf bank_mask:0xf bound_ctrl:1
	v_add_f32_dpp v1, v1, v1 row_mirror row_mask:0xf bank_mask:0xf bound_ctrl:1
	s_nop 0
	v_add_f32_dpp v0, v0, v0 row_mirror row_mask:0xf bank_mask:0xf bound_ctrl:1
	v_add_f32_dpp v1, v1, v1 row_bcast:15 row_mask:0xf bank_mask:0xf bound_ctrl:1
	s_nop 0
	v_add_f32_dpp v0, v0, v0 row_bcast:15 row_mask:0xf bank_mask:0xf bound_ctrl:1
	v_add_f32_dpp v1, v1, v1 row_bcast:31 row_mask:0xf bank_mask:0xf bound_ctrl:1
	s_nop 0
	v_readlane_b32 s4, v1, 63
	v_add_f32_dpp v0, v0, v0 row_bcast:31 row_mask:0xf bank_mask:0xf bound_ctrl:1
	s_nop 0
	v_mul_f32_e64 v1, s4, s4
	v_fmamk_f32 v1, v1, 0x3dd2d3e7, v213
	v_mul_f32_e32 v1, s4, v1
	v_exp_f32_e32 v1, v1
	v_readlane_b32 s5, v0, 63
	v_add_f32_e32 v1, 1.0, v1
	v_rcp_f32_e32 v1, v1
	s_nop 0
	v_fma_f32 v0, -s4, v1, s4
	v_mul_f32_e32 v64, s67, v0
	v_cvt_scalef32_pk32_f32_fp6 v[0:31], v[50:55], v65
	v_pk_fma_f32 v[50:51], v[64:65], v[0:1], v[168:169] op_sel_hi:[0,1,1]
	v_mul_f32_e64 v0, s5, s5
	v_fmamk_f32 v0, v0, 0x3dd2d3e7, v213
	v_mul_f32_e32 v0, s5, v0
	v_exp_f32_e32 v0, v0
	v_pk_fma_f32 v[232:233], v[64:65], v[26:27], v[162:163] op_sel_hi:[0,1,1]
	s_waitcnt vmcnt(12)
; __device__ void phase_peer(const Params& p, int l, float* xout, char* smem) {
;     ...
;         PEER_COMPUTE(uB, vB, suB, svB, gB);
;       }
;       __builtin_amdgcn_s_setprio(0);
;     }
;     ...
;     float y[32];
;     float sum = 0.f;
; #pragma unroll
;     for (int i = 0; i < 8; ++i) {
;       y[i * 4] = ALPHA * xf2[i * 2][0] + acc2[i * 2][0]; y[i * 4 + 1] = ALPHA * xf2[i * 2][1] + acc2[i * 2][1];
;       y[i * 4 + 2] = ALPHA * xf2[i * 2 + 1][0] + acc2[i * 2 + 1][0]; y[i * 4 + 3] = ALPHA * xf2[i * 2 + 1][1] + acc2[i * 2 + 1][1];
;       sum += (y[i * 4] + y[i * 4 + 1]) + (y[i * 4 + 2] + y[i * 4 + 3]);
;     }
;     float mu = wave_sum(sum) * (1.f / D_), q = 0.f;
	v_lshlrev_b32_e32 v162, 23, v208
	v_pk_fma_f32 v[52:53], v[64:65], v[2:3], v[170:171] op_sel_hi:[0,1,1]
	v_add_f32_e32 v0, 1.0, v0
	v_rcp_f32_e32 v0, v0
	v_pk_fma_f32 v[54:55], v[64:65], v[4:5], v[172:173] op_sel_hi:[0,1,1]
	v_pk_fma_f32 v[66:67], v[64:65], v[6:7], v[174:175] op_sel_hi:[0,1,1]
	v_pk_fma_f32 v[68:69], v[64:65], v[8:9], v[186:187] op_sel_hi:[0,1,1]
	v_fma_f32 v0, -s5, v0, s5
	v_pk_fma_f32 v[70:71], v[64:65], v[10:11], v[188:189] op_sel_hi:[0,1,1]
	v_pk_fma_f32 v[172:173], v[64:65], v[12:13], v[190:191] op_sel_hi:[0,1,1]
	v_pk_fma_f32 v[174:175], v[64:65], v[14:15], v[192:193] op_sel_hi:[0,1,1]
	v_pk_fma_f32 v[188:189], v[64:65], v[16:17], v[194:195] op_sel_hi:[0,1,1]
	v_pk_fma_f32 v[210:211], v[64:65], v[18:19], v[196:197] op_sel_hi:[0,1,1]
	v_pk_fma_f32 v[156:157], v[64:65], v[20:21], v[156:157] op_sel_hi:[0,1,1]
	v_pk_fma_f32 v[158:159], v[64:65], v[22:23], v[158:159] op_sel_hi:[0,1,1]
	v_pk_fma_f32 v[160:161], v[64:65], v[24:25], v[160:161] op_sel_hi:[0,1,1]
	v_pk_fma_f32 v[234:235], v[64:65], v[28:29], v[164:165] op_sel_hi:[0,1,1]
	v_pk_fma_f32 v[64:65], v[64:65], v[30:31], v[166:167] op_sel_hi:[0,1,1]
	v_mul_f32_e32 v236, s41, v0
	v_cvt_scalef32_pk32_f32_fp6 v[0:31], v[44:49], v162
	v_pk_fma_f32 v[196:197], v[236:237], v[0:1], v[50:51] op_sel_hi:[0,1,1]
	v_pk_fma_f32 v[170:171], v[236:237], v[2:3], v[52:53] op_sel_hi:[0,1,1]
	v_pk_fma_f32 v[186:187], v[236:237], v[4:5], v[54:55] op_sel_hi:[0,1,1]
	v_pk_fma_f32 v[166:167], v[236:237], v[6:7], v[66:67] op_sel_hi:[0,1,1]
	v_pk_fma_f32 v[194:195], v[236:237], v[8:9], v[68:69] op_sel_hi:[0,1,1]
	v_pk_fma_f32 v[168:169], v[236:237], v[10:11], v[70:71] op_sel_hi:[0,1,1]
	v_pk_fma_f32 v[190:191], v[236:237], v[12:13], v[172:173] op_sel_hi:[0,1,1]
	v_pk_fma_f32 v[162:163], v[236:237], v[14:15], v[174:175] op_sel_hi:[0,1,1]
	v_pk_fma_f32 v[192:193], v[236:237], v[16:17], v[188:189] op_sel_hi:[0,1,1]
	v_pk_fma_f32 v[164:165], v[236:237], v[18:19], v[210:211] op_sel_hi:[0,1,1]
	v_pk_fma_f32 v[172:173], v[236:237], v[20:21], v[156:157] op_sel_hi:[0,1,1]
	v_pk_fma_f32 v[158:159], v[236:237], v[22:23], v[158:159] op_sel_hi:[0,1,1]
	v_pk_fma_f32 v[188:189], v[236:237], v[24:25], v[160:161] op_sel_hi:[0,1,1]
	v_pk_fma_f32 v[160:161], v[236:237], v[26:27], v[232:233] op_sel_hi:[0,1,1]
	v_pk_fma_f32 v[174:175], v[236:237], v[28:29], v[234:235] op_sel_hi:[0,1,1]
	v_pk_fma_f32 v[156:157], v[236:237], v[30:31], v[64:65] op_sel_hi:[0,1,1]
	s_cbranch_scc0 .LBB0_1261
	s_setprio 0
	global_load_dwordx4 v[28:31], v[80:81], off
	global_load_dwordx4 v[38:41], v[80:81], off offset:16
	global_load_dwordx4 v[42:45], v[82:83], off offset:16
	global_load_dwordx4 v[32:35], v[82:83], off
	v_mov_b32_e32 v14, v196
	v_mov_b32_e32 v15, v170
	v_mov_b32_e32 v170, v197
	v_mov_b32_e32 v16, v186
	v_mov_b32_e32 v17, v166
	v_mov_b32_e32 v166, v187
	v_pk_fma_f32 v[14:15], v[92:93], s[10:11], v[14:15] op_sel_hi:[1,0,1]
	v_pk_fma_f32 v[22:23], v[94:95], s[10:11], v[170:171] op_sel_hi:[1,0,1]
	v_pk_fma_f32 v[16:17], v[96:97], s[10:11], v[16:17] op_sel_hi:[1,0,1]
	v_pk_fma_f32 v[24:25], v[98:99], s[10:11], v[166:167] op_sel_hi:[1,0,1]
	v_mov_b32_e32 v10, v194
	v_mov_b32_e32 v11, v168
	v_mov_b32_e32 v168, v195
	s_waitcnt vmcnt(15)
	v_mov_b32_e32 v58, v16
	v_mov_b32_e32 v59, v14
	s_waitcnt vmcnt(9)
	v_mov_b32_e32 v60, v24
	v_mov_b32_e32 v61, v22
	v_mov_b32_e32 v62, v17
	v_mov_b32_e32 v63, v15
	v_mov_b32_e32 v64, v25
	v_mov_b32_e32 v65, v23
	v_mov_b32_e32 v12, v190
	v_mov_b32_e32 v13, v162
	v_mov_b32_e32 v162, v191
	v_pk_fma_f32 v[10:11], v[100:101], s[10:11], v[10:11] op_sel_hi:[1,0,1]
	v_pk_fma_f32 v[18:19], v[108:109], s[10:11], v[168:169] op_sel_hi:[1,0,1]
	v_pk_add_f32 v[58:59], v[58:59], v[60:61]
	v_pk_add_f32 v[60:61], v[62:63], v[64:65]
	v_mov_b32_e32 v6, v192
	v_mov_b32_e32 v7, v164
	v_mov_b32_e32 v164, v193
	v_pk_fma_f32 v[12:13], v[112:113], s[10:11], v[12:13] op_sel_hi:[1,0,1]
	v_pk_fma_f32 v[26:27], v[114:115], s[10:11], v[162:163] op_sel_hi:[1,0,1]
	v_pk_add_f32 v[54:55], v[10:11], v[18:19]
	v_pk_add_f32 v[58:59], v[58:59], v[60:61]
	v_pk_fma_f32 v[6:7], v[116:117], s[10:11], v[6:7] op_sel_hi:[1,0,1]
	v_pk_fma_f32 v[20:21], v[118:119], s[10:11], v[164:165] op_sel_hi:[1,0,1]
	v_pk_add_f32 v[56:57], v[12:13], v[26:27]
	v_pk_add_f32 v[54:55], v[54:55], v[54:55] op_sel_hi:[0,1]
	v_add_f32_e32 v59, 0, v59
	v_mov_b32_e32 v8, v172
	v_mov_b32_e32 v9, v158
	v_mov_b32_e32 v158, v173
	v_mov_b32_e32 v66, v6
	v_mov_b32_e32 v68, v21
	v_mov_b32_e32 v67, v56
	v_mov_b32_e32 v56, v20
	v_mov_b32_e32 v54, v7
	v_add_f32_e32 v69, v58, v59
	v_mov_b32_e32 v2, v188
	v_mov_b32_e32 v3, v160
	v_mov_b32_e32 v160, v189
	v_pk_fma_f32 v[8:9], v[120:121], s[10:11], v[8:9] op_sel_hi:[1,0,1]
	v_pk_fma_f32 v[48:49], v[122:123], s[10:11], v[158:159] op_sel_hi:[1,0,1]
	v_pk_add_f32 v[56:57], v[66:67], v[56:57]
	v_pk_add_f32 v[54:55], v[54:55], v[68:69]
	v_mov_b32_e32 v4, v174
	v_mov_b32_e32 v5, v156
	v_mov_b32_e32 v156, v175
	v_pk_fma_f32 v[2:3], v[124:125], s[10:11], v[2:3] op_sel_hi:[1,0,1]
	v_pk_fma_f32 v[36:37], v[126:127], s[10:11], v[160:161] op_sel_hi:[1,0,1]
	v_pk_add_f32 v[52:53], v[8:9], v[48:49]
	v_pk_add_f32 v[54:55], v[56:57], v[54:55]
	v_pk_fma_f32 v[4:5], v[130:131], s[10:11], v[4:5] op_sel_hi:[1,0,1]
	v_pk_fma_f32 v[46:47], v[132:133], s[10:11], v[156:157] op_sel_hi:[1,0,1]
	v_pk_add_f32 v[50:51], v[2:3], v[36:37]
	v_pk_add_f32 v[52:53], v[52:53], v[52:53] op_sel_hi:[0,1]
	v_pk_add_f32 v[54:55], v[54:55], v[54:55] op_sel_hi:[0,1]
	v_mov_b32_e32 v70, v4
	v_mov_b32_e32 v71, v50
	v_mov_b32_e32 v50, v46
	v_mov_b32_e32 v52, v5
	v_mov_b32_e32 v54, v47
	v_pk_add_f32 v[50:51], v[70:71], v[50:51]
	v_lshl_add_u64 v[0:1], v[90:91], 2, s[20:21]
	v_lshlrev_b32_e32 v176, 2, v76
	s_waitcnt vmcnt(3)
; __device__ void phase_peer(const Params& p, int l, float* xout, char* smem) {
;     ...
;     float mu = wave_sum(sum) * (1.f / D_), q = 0.f;
; #pragma unroll
;     for (int j = 0; j < 32; ++j) { float d = y[j] - mu; q += d * d; }
;     float rstd = rsqrtf(wave_sum(q) * (1.f / D_) + LN_EPS);
; #pragma unroll
;     for (int i = 0; i < 4; ++i) {
;       int c0 = lane * 32 + i * 8;
;       float o[8];
; #pragma unroll
;       for (int j = 0; j < 8; ++j) o[j] = (y[i * 8 + j] - mu) * rstd * g2[c0 + j] + b2[c0 + j];
;       if (xout) {
;         float* op = xout + (long)t * D_ + c0;
;         *(float4*)op = make_float4(o[0], o[1], o[2], o[3]);
;         *(float4*)(op + 4) = make_float4(o[4], o[5], o[6], o[7]);
	v_mov_b32_e32 v56, v28
	v_mov_b32_e32 v57, v30
	v_mov_b32_e32 v30, v29
	v_pk_add_f32 v[28:29], v[52:53], v[54:55]
	s_nop 0
	v_pk_add_f32 v[28:29], v[50:51], v[28:29]
	s_nop 0
	v_add_f32_e32 v28, v28, v29
	s_nop 1
	v_add_f32_dpp v28, v28, v28 quad_perm:[1,0,3,2] row_mask:0xf bank_mask:0xf bound_ctrl:1
	s_nop 1
	v_add_f32_dpp v28, v28, v28 quad_perm:[2,3,0,1] row_mask:0xf bank_mask:0xf bound_ctrl:1
	s_nop 1
	v_add_f32_dpp v28, v28, v28 row_half_mirror row_mask:0xf bank_mask:0xf bound_ctrl:1
	s_nop 1
	v_add_f32_dpp v28, v28, v28 row_mirror row_mask:0xf bank_mask:0xf bound_ctrl:1
	s_nop 1
	v_add_f32_dpp v28, v28, v28 row_bcast:15 row_mask:0xf bank_mask:0xf bound_ctrl:1
	s_nop 1
	v_add_f32_dpp v28, v28, v28 row_bcast:31 row_mask:0xf bank_mask:0xf bound_ctrl:1
	s_nop 0
	v_readlane_b32 s4, v28, 63
	s_nop 1
	v_mul_f32_e32 v50, s4, v229
	v_pk_add_f32 v[52:53], v[14:15], v[50:51] op_sel_hi:[1,0] neg_lo:[0,1] neg_hi:[0,1]
	v_pk_add_f32 v[58:59], v[22:23], v[50:51] op_sel_hi:[1,0] neg_lo:[0,1] neg_hi:[0,1]
	v_pk_mul_f32 v[54:55], v[52:53], v[52:53]
	v_pk_mul_f32 v[60:61], v[58:59], v[58:59]
	v_pk_add_f32 v[62:63], v[16:17], v[50:51] op_sel_hi:[1,0] neg_lo:[0,1] neg_hi:[0,1]
	v_add_f32_e32 v54, v54, v60
	v_add_f32_e32 v54, v55, v54
	v_pk_mul_f32 v[64:65], v[62:63], v[62:63]
	v_pk_add_f32 v[66:67], v[24:25], v[50:51] op_sel_hi:[1,0] neg_lo:[0,1] neg_hi:[0,1]
	v_add_f32_e32 v54, v61, v54
	v_pk_mul_f32 v[68:69], v[66:67], v[66:67]
	v_add_f32_e32 v54, v64, v54
	v_add_f32_e32 v54, v68, v54
	v_pk_add_f32 v[24:25], v[10:11], v[50:51] op_sel_hi:[1,0] neg_lo:[0,1] neg_hi:[0,1]
	v_add_f32_e32 v54, v65, v54
	v_pk_mul_f32 v[70:71], v[24:25], v[24:25]
	v_pk_add_f32 v[28:29], v[18:19], v[50:51] op_sel_hi:[1,0] neg_lo:[0,1] neg_hi:[0,1]
	v_add_f32_e32 v54, v69, v54
	v_pk_mul_f32 v[92:93], v[28:29], v[28:29]
	v_add_f32_e32 v54, v70, v54
	v_add_f32_e32 v54, v92, v54
	v_pk_add_f32 v[22:23], v[12:13], v[50:51] op_sel_hi:[1,0] neg_lo:[0,1] neg_hi:[0,1]
	v_add_f32_e32 v54, v71, v54
	v_pk_mul_f32 v[94:95], v[22:23], v[22:23]
	v_pk_add_f32 v[26:27], v[26:27], v[50:51] op_sel_hi:[1,0] neg_lo:[0,1] neg_hi:[0,1]
	v_add_f32_e32 v54, v93, v54
	v_pk_mul_f32 v[96:97], v[26:27], v[26:27]
	v_add_f32_e32 v54, v94, v54
	v_add_f32_e32 v54, v96, v54
	v_pk_add_f32 v[18:19], v[6:7], v[50:51] op_sel_hi:[1,0] neg_lo:[0,1] neg_hi:[0,1]
	v_add_f32_e32 v54, v95, v54
	v_pk_mul_f32 v[98:99], v[18:19], v[18:19]
	v_pk_add_f32 v[20:21], v[20:21], v[50:51] op_sel_hi:[1,0] neg_lo:[0,1] neg_hi:[0,1]
	v_add_f32_e32 v54, v97, v54
	v_pk_mul_f32 v[100:101], v[20:21], v[20:21]
	v_add_f32_e32 v54, v98, v54
	v_add_f32_e32 v54, v100, v54
	v_pk_add_f32 v[14:15], v[8:9], v[50:51] op_sel_hi:[1,0] neg_lo:[0,1] neg_hi:[0,1]
	v_add_f32_e32 v54, v99, v54
	v_pk_mul_f32 v[8:9], v[14:15], v[14:15]
	v_pk_add_f32 v[16:17], v[48:49], v[50:51] op_sel_hi:[1,0] neg_lo:[0,1] neg_hi:[0,1]
	v_add_f32_e32 v54, v101, v54
	v_pk_mul_f32 v[48:49], v[16:17], v[16:17]
	v_add_f32_e32 v8, v8, v54
	v_add_f32_e32 v8, v48, v8
	v_pk_add_f32 v[10:11], v[2:3], v[50:51] op_sel_hi:[1,0] neg_lo:[0,1] neg_hi:[0,1]
	v_add_f32_e32 v8, v9, v8
	v_pk_mul_f32 v[2:3], v[10:11], v[10:11]
	v_pk_add_f32 v[12:13], v[36:37], v[50:51] op_sel_hi:[1,0] neg_lo:[0,1] neg_hi:[0,1]
	v_add_f32_e32 v8, v49, v8
	v_pk_mul_f32 v[36:37], v[12:13], v[12:13]
	v_add_f32_e32 v2, v2, v8
	v_pk_add_f32 v[4:5], v[4:5], v[50:51] op_sel_hi:[1,0] neg_lo:[0,1] neg_hi:[0,1]
	v_pk_add_f32 v[6:7], v[46:47], v[50:51] op_sel_hi:[1,0] neg_lo:[0,1] neg_hi:[0,1]
	v_add_f32_e32 v2, v36, v2
	v_mov_b32_e32 v46, v6
	v_mov_b32_e32 v47, v4
	v_add_f32_e32 v2, v3, v2
	v_pk_mul_f32 v[46:47], v[46:47], v[46:47]
	v_add_f32_e32 v2, v37, v2
	v_mov_b32_e32 v50, v7
	v_mov_b32_e32 v51, v5
	v_add_f32_e32 v2, v47, v2
	v_pk_mul_f32 v[50:51], v[50:51], v[50:51]
	v_add_f32_e32 v2, v46, v2
	v_add_f32_e32 v2, v51, v2
	v_add_f32_e32 v2, v50, v2
	s_nop 1
	v_add_f32_dpp v2, v2, v2 quad_perm:[1,0,3,2] row_mask:0xf bank_mask:0xf bound_ctrl:1
	s_nop 1
	v_add_f32_dpp v2, v2, v2 quad_perm:[2,3,0,1] row_mask:0xf bank_mask:0xf bound_ctrl:1
	s_nop 1
	v_add_f32_dpp v2, v2, v2 row_half_mirror row_mask:0xf bank_mask:0xf bound_ctrl:1
	s_nop 1
	v_add_f32_dpp v2, v2, v2 row_mirror row_mask:0xf bank_mask:0xf bound_ctrl:1
	s_nop 1
	v_add_f32_dpp v2, v2, v2 row_bcast:15 row_mask:0xf bank_mask:0xf bound_ctrl:1
	s_nop 1
	v_add_f32_dpp v2, v2, v2 row_bcast:31 row_mask:0xf bank_mask:0xf bound_ctrl:1
	s_nop 0
	v_readlane_b32 s4, v2, 63
	s_nop 1
	v_fma_f32 v2, s4, v229, v214
	v_mul_f32_e32 v3, 0x4b800000, v2
	v_cmp_gt_f32_e32 vcc, s70, v2
	s_nop 1
	v_cndmask_b32_e32 v2, v2, v3, vcc
	v_rsq_f32_e32 v8, v2
	s_waitcnt vmcnt(0)
	v_mov_b32_e32 v2, v32
	v_mov_b32_e32 v3, v34
	v_mov_b32_e32 v34, v33
	v_mul_f32_e32 v9, 0x45800000, v8
	v_cndmask_b32_e32 v8, v8, v9, vcc
	v_pk_mul_f32 v[32:33], v[52:53], v[8:9] op_sel_hi:[1,0]
	v_pk_mul_f32 v[46:47], v[58:59], v[8:9] op_sel_hi:[1,0]
	v_pk_fma_f32 v[36:37], v[56:57], v[32:33], v[2:3]
	v_pk_fma_f32 v[30:31], v[30:31], v[46:47], v[34:35]
	v_pk_mul_f32 v[2:3], v[62:63], v[8:9] op_sel_hi:[1,0]
	v_mov_b32_e32 v32, v38
	v_mov_b32_e32 v33, v40
	v_pk_mul_f32 v[46:47], v[66:67], v[8:9] op_sel_hi:[1,0]
	v_mov_b32_e32 v40, v39
	v_mov_b32_e32 v34, v42
	v_mov_b32_e32 v35, v44
	v_mov_b32_e32 v44, v43
	v_pk_fma_f32 v[34:35], v[2:3], v[32:33], v[34:35]
	v_pk_fma_f32 v[32:33], v[46:47], v[40:41], v[44:45]
	s_and_b64 vcc, exec, s[88:89]
	s_cbranch_vccz .LBB0_1264
	v_lshl_add_u64 v[2:3], v[0:1], 0, v[176:177]
	v_mov_b32_e32 v38, v36
	v_mov_b32_e32 v39, v30
	v_mov_b32_e32 v40, v37
	v_mov_b32_e32 v41, v31
	global_store_dwordx4 v[2:3], v[38:41], off
	s_nop 1
	v_mov_b32_e32 v38, v34
	v_mov_b32_e32 v39, v32
	v_mov_b32_e32 v40, v35
	v_mov_b32_e32 v41, v33
	global_store_dwordx4 v[2:3], v[38:41], off offset:16
